# v42 + HGRN LDS bank-conflict fix: bit-4 XOR swizzle (row bit2^bit3) of the 144-byte-pitch operand images; fragment reads modelled 8->4 LDS cycles
# speedup vs baseline: 1.0096x; 1.0007x over previous
; __device__ __forceinline__ void hgrn_phase(const Params& p, int e, char* lds) {
;     ...
;   char* QD = lds + OFF_QD; char* QA = lds + OFF_QA; char* KB = lds + OFF_KB; char* KS = lds + OFF_KS; char* VT = lds + OFF_VT; char* PP = lds + OFF_P; char* ST = lds + OFF_ST;
;   char* RQ = QD; char* RZ = QA; char* RV = KB;
;   float* TOT = (float*)(lds + OFF_TOT); float* DD = (float*)(lds + OFF_D);
;   const int k = tid & 63, rq = tid >> 6;
;   const int vv = tid & 127, jg = tid >> 7;
;   const int lr = tid >> 3, lc8 = (tid & 7) * 8;
;   const int vr = tid >> 4, vc8 = (tid & 15) * 8;
;   for (int u = blockIdx.x; u < 256; u += gridDim.x) {
;     const int kh = u & 1, dir = (u >> 1) & 1, h = (u >> 2) & 3, b = u >> 4;
;     float lbk = 0.f;
;     if (e != 0) { const float* lbsrc = dir ? p.lb_bwd : p.lb_fwd; const float a0 = lbsrc[h * 128 + kh * 64 + k], a1 = lbsrc[512 + h * 128 + kh * 64 + k]; lbk = 1.0f / (1.0f + __expf(a0 - a1)); }
;     const int rsb = dir ? -8192 : 8192;
;     const int base0 = (b * SEQ + (dir ? (SEQ - 1) : 0)) * 8192;
;     const int qcol = (1536 + h * 128 + kh * 64 + lc8) * 2, zcol = ((dir ? 2560 : 2048) + h * 128 + kh * 64 + lc8) * 2, vcol = (3072 + h * 128 + vc8) * 2;
;     const int osb = dir ? -1024 : 1024;
;     const int obase = (dir * 2 + kh) * (T * 1024) + (b * SEQ + (dir ? (SEQ - 1) : 0)) * 1024 + h * 256;
;     f32x4 Sacc[4];
; #pragma unroll
;     for (int i = 0; i < 4; ++i) Sacc[i] = (f32x4){0.f, 0.f, 0.f, 0.f};
;     for (int i = tid; i < 128 * PK / 16; i += 512) *(u32x4*)(ST + i * 16) = (u32x4){0, 0, 0, 0};
.LBB0_208:
	s_andn2_b64 vcc, exec, s[46:47]
	s_cbranch_vccnz .LBB0_459
	v_readlane_b32 s0, v255, 25
	s_cmp_gt_i32 s0, 0
	s_mov_b64 s[0:1], -1
	s_cbranch_scc0 .LBB0_399
	v_readlane_b32 s0, v252, 20
	v_readlane_b32 s1, v252, 21
	v_mov_b32_e32 v0, v232
	s_andn2_b64 vcc, exec, s[0:1]
	s_cbranch_vccnz .LBB0_242
	s_waitcnt lgkmcnt(0)
	v_ashrrev_i32_e32 v3, 6, v0
	v_and_b32_e32 v15, 1, v3
	v_ashrrev_i32_e32 v4, 7, v0
	v_lshlrev_b32_e32 v17, 1, v15
	v_cmp_le_i32_e64 s[44:45], v4, v17
	v_or_b32_e32 v17, 1, v17
	v_cmp_le_i32_e64 s[46:47], v4, v17
	v_lshrrev_b32_e32 v17, 2, v0
	v_ashrrev_i32_e32 v103, 3, v0
	s_waitcnt lgkmcnt(0)
	v_lshlrev_b32_e32 v1, 3, v0
	s_movk_i32 s4, 0x90
	v_lshlrev_b32_e32 v10, 4, v4
	v_and_b32_e32 v17, 12, v17
	v_and_b32_e32 v102, 63, v0
	v_and_b32_e32 v104, 56, v1
	v_ashrrev_i32_e32 v105, 4, v0
	v_and_b32_e32 v106, 0x78, v1
	v_and_b32_e32 v1, 15, v0
	v_mul_lo_u32 v2, v103, s4
	s_movk_i32 s2, 0x110
	v_or_b32_e32 v112, v10, v17
	v_add_u32_e32 v6, 0, v2
	v_mul_lo_u32 v2, v105, s2
	v_readlane_b32 s2, v254, 33
	v_lshlrev_b32_e32 v12, 2, v102
	v_lshl_or_b32 v19, v15, 5, v1
	v_or_b32_e32 v113, 2, v112
	v_or_b32_e32 v114, 3, v112
	v_lshl_add_u32 v107, v0, 2, s2
	v_add_u32_e32 v108, s2, v12
	v_readlane_b32 s2, v254, 34
	v_or_b32_e32 v18, v10, v1
	v_mad_u32_u24 v111, v19, s4, 0
	v_cmp_gt_i32_e64 s[48:49], v112, v19
	v_cmp_lt_i32_e64 s[50:51], v112, v19
	v_cmp_gt_i32_e64 s[52:53], v113, v19
	v_cmp_gt_i32_e64 s[54:55], v114, v19
	v_or_b32_e32 v10, 16, v19
	v_lshlrev_b32_e32 v19, 6, v4
	v_lshlrev_b32_e32 v17, 2, v17
	s_movk_i32 s5, 0x480
	v_add_u32_e32 v8, 0, v2
	v_lshl_add_u32 v2, v102, 1, 0
	v_add_u32_e32 v109, s2, v12
	s_movk_i32 s8, 0x8e
	v_lshlrev_b32_e32 v16, 2, v15
	v_add3_u32 v116, s2, v19, v17
	s_movk_i32 s2, 0x1100
	v_and_b32_e32 v5, 0x7f, v0
	v_readlane_b32 s0, v255, 26
	v_mad_u32_u24 v12, v102, s8, v2
	v_lshlrev_b32_e32 v14, 5, v4
	v_mad_u64_u32 v[100:101], s[26:27], v3, s5, v[2:3]
	v_mul_lo_u32 v2, v4, s2
	v_or_b32_e32 v4, 1, v16
	v_or_b32_e32 v20, 2, v16
	v_or_b32_e32 v16, 3, v16
	v_readlane_b32 s2, v254, 35
	s_add_i32 s0, s0, 9
	v_cmp_gt_i32_e64 s[40:41], s5, v0
	v_lshl_add_u32 v11, v5, 1, 0
	v_cmp_gt_u32_e64 s[42:43], 64, v0
	v_lshlrev_b32_e32 v13, 4, v3
	v_and_b32_e32 v110, 48, v0
	v_lshrrev_b32_e32 v180, 1, v0
	v_xor_b32_e32 v180, v180, v0
	v_and_b32_e32 v180, 4, v180
	v_lshlrev_b32_e32 v180, 2, v180
	v_xor_b32_e32 v110, v110, v180
	v_xor_b32_e32 v13, v13, v180
	v_lshrrev_b32_e32 v181, 2, v0
	v_and_b32_e32 v181, 16, v181
	v_xor_b32_e32 v181, v100, v181
	v_xor_b32_e32 v182, 16, v181
	v_mul_lo_u32 v18, v18, s4
	v_cmp_lt_i32_e64 s[64:65], 0, v3
	v_cmp_lt_i32_e64 s[66:67], 1, v3
	v_cmp_lt_i32_e64 s[68:69], 2, v3
	v_cmp_lt_i32_e64 s[70:71], 3, v3
	v_cmp_lt_i32_e64 s[72:73], 4, v3
	v_cmp_lt_i32_e64 s[74:75], 5, v3
	v_cmp_lt_i32_e64 s[76:77], 6, v3
	v_lshl_or_b32 v3, v15, 6, v1
	v_lshl_or_b32 v19, v4, 4, v1
	v_lshl_or_b32 v21, v20, 4, v1
	v_lshl_or_b32 v22, v16, 4, v1
	v_lshlrev_b32_e32 v124, 5, v4
	v_mov_b32_e32 v4, s2
	v_add_u32_e32 v129, 0xfffffe00, v0
	v_lshlrev_b32_e32 v0, 4, v0
	v_readlane_b32 s1, v255, 27
	s_cmp_gt_u32 s0, 20
	v_lshlrev_b32_e32 v7, 1, v104
	v_lshlrev_b32_e32 v9, 1, v106
	v_mad_u32_u24 v5, v5, s8, v11
	v_add_u32_e32 v18, 0, v18
	v_lshlrev_b32_e32 v115, 1, v112
	v_xor_b32_e32 v115, v115, v180
	v_cmp_gt_i32_e64 s[56:57], v112, v10
	v_cmp_lt_i32_e64 s[58:59], v112, v10
	v_cmp_gt_i32_e64 s[60:61], v113, v10
	v_cmp_gt_i32_e64 s[62:63], v114, v10
	v_add_u32_e32 v10, 0x900, v111
	v_or_b32_e32 v17, 64, v110
	v_lshlrev_b32_e32 v118, 1, v1
	v_mul_u32_u24_e32 v101, 0x90, v3
	v_mul_u32_u24_e32 v119, 0x90, v19
	v_mad_u32_u24 v23, v3, s4, 0
	v_mad_u32_u24 v24, v19, s4, 0
	v_mad_u32_u24 v25, v21, s4, 0
	v_mad_u32_u24 v26, v22, s4, 0
	v_lshlrev_b32_e32 v123, 7, v15
	v_lshlrev_b32_e32 v126, 5, v16
	v_add_u32_e32 v127, s2, v110
	v_mad_u32_u24 v3, v3, s4, v4
	v_mad_u32_u24 v15, v19, s4, v4
	v_mad_u32_u24 v16, v21, s4, v4
	v_mad_u32_u24 v4, v22, s4, v4
	v_readlane_b32 s2, v254, 36
	v_mov_b32_e32 v19, 0x1800
	v_and_b32_e32 v136, 0x70, v0
	v_readlane_b32 s4, v255, 14
	s_cselect_b64 s[0:1], -1, 0
	v_add_u32_e32 v117, 0, v115
	v_mul_u32_u24_e32 v120, 0x90, v21
	v_mul_u32_u24_e32 v121, 0x90, v22
	v_add_u32_e32 v122, 0, v110
	v_lshlrev_b32_e32 v125, 5, v20
	v_add_u32_e32 v128, 0xfc0, v112
	v_add_u32_e32 v130, s2, v0
	v_or_b32_e32 v131, v123, v118
	v_or_b32_e32 v132, 1, v112
	v_lshl_or_b32 v133, v1, 4, v19
	v_add_u32_e32 v134, 0x60, v105
	v_add_u32_e32 v135, 64, v105
	v_add_u32_e32 v137, 64, v103
	v_or_b32_e32 v138, 0xc00, v136
	v_add_u32_e32 v139, v3, v17
	v_add_u32_e32 v140, v15, v17
	v_add_u32_e32 v141, v16, v17
	v_add_u32_e32 v142, v4, v17
	v_add_u32_e32 v143, v6, v7
	v_add_u32_e32 v152, v8, v9
	v_add_u32_e32 v153, v11, v2
	v_add_u32_e32 v154, v12, v13
	v_add_u32_e32 v155, v5, v14
	v_sub_u32_e32 v183, v155, v180
	v_add_u32_e32 v155, v155, v180
	v_add_u32_e32 v156, v18, v110
	v_add_u32_e32 v157, v10, v115
	v_add_u32_e32 v158, v23, v110
	v_add_u32_e32 v159, v24, v110
	v_add_u32_e32 v160, v25, v110
	v_add_u32_e32 v161, v26, v110
	v_readlane_b32 s2, v254, 29
	v_readlane_b32 s39, v254, 27
	s_mov_b32 s36, s4
	v_readlane_b32 s5, v255, 15
	s_branch .LBB0_213

; __device__ __forceinline__ float bf2f(unsigned short b) { return __uint_as_float(((unsigned)b) << 16); }
; #define LBAR() do { asm volatile("s_waitcnt lgkmcnt(0)" ::: "memory"); __builtin_amdgcn_s_barrier(); asm volatile("" ::: "memory"); } while (0)
; __device__ __forceinline__ void hgrn_phase(const Params& p, int e, char* lds) {
;     ...
;       *(u32x4*)(RQ + lr * PK + lc8 * 2) = gq; *(u32x4*)(RZ + lr * PK + lc8 * 2) = gz;
;       *(u32x4*)(RV + vr * PV + vc8 * 2) = gv0; *(u32x4*)(RV + (vr + 32) * PV + vc8 * 2) = gv1;
;       LBAR();
;       float qf[8], kk[8], cl[8]; float run = 0.f;
; #pragma unroll
;       for (int i = 0; i < 8; ++i) { const int t = 8 * rq + i; const float z = bf2f(*(const unsigned short*)(RZ + t * PK + k * 2)); qf[i] = bf2f(*(const unsigned short*)(RQ + t * PK + k * 2));
;         const float sg = __builtin_amdgcn_rcpf(1.0f + __builtin_amdgcn_exp2f(-L2E * z)); const float f = lbk + (1.0f - lbk) * sg;
;         run += __builtin_amdgcn_logf(f); cl[i] = run; kk[i] = 1.0f - f; }
;       TOT[rq * 64 + k] = run;
;       unsigned short rvv[16];
; #pragma unroll
;       for (int i = 0; i < 16; ++i) rvv[i] = *(const unsigned short*)(RV + (16 * jg + i) * PV + vv * 2);
;       u32x4 vpa, vpb;
;       vpa.x = rvv[0] | ((unsigned)rvv[1] << 16); vpa.y = rvv[2] | ((unsigned)rvv[3] << 16); vpa.z = rvv[4] | ((unsigned)rvv[5] << 16); vpa.w = rvv[6] | ((unsigned)rvv[7] << 16);
;       vpb.x = rvv[8] | ((unsigned)rvv[9] << 16); vpb.y = rvv[10] | ((unsigned)rvv[11] << 16); vpb.z = rvv[12] | ((unsigned)rvv[13] << 16); vpb.w = rvv[14] | ((unsigned)rvv[15] << 16);
;       LBAR();
;       { float tt[8];
; #pragma unroll
;         for (int r8 = 0; r8 < 8; ++r8) tt[r8] = TOT[r8 * 64 + k];
;         const float mid = (tt[0] + tt[1]) + (tt[2] + tt[3]), last = mid + ((tt[4] + tt[5]) + (tt[6] + tt[7]));
;         float off = 0.f;
; #pragma unroll
;         for (int r8 = 0; r8 < 7; ++r8) off += (r8 < rq) ? tt[r8] : 0.f;
;         const float el = __builtin_amdgcn_exp2f(last), em = __builtin_amdgcn_exp2f(fminf(-mid, 120.f)), emi = __builtin_amdgcn_exp2f(mid);
;         if (rq == 0) DD[k] = el;
.LBB0_222:
	s_waitcnt vmcnt(16)
	ds_write_b128 v143, v[16:19]
	ds_write_b128 v143, v[20:23] offset:9216
	ds_write_b128 v152, v[24:27] offset:18432
	ds_write_b128 v152, v[28:31] offset:27136
	s_waitcnt lgkmcnt(0)
	s_barrier
	ds_read_u16 v16, v100 offset:9216
	ds_read_u16 v17, v100 offset:9360
	ds_read_u16 v18, v100 offset:9504
	ds_read_u16 v19, v100 offset:9648
	ds_read_u16 v20, v100 offset:9792
	ds_read_u16 v21, v100 offset:9936
	ds_read_u16 v22, v100 offset:10080
	ds_read_u16 v23, v100 offset:10224
	s_waitcnt lgkmcnt(6)
	v_lshlrev_b32_e32 v17, 16, v17
	v_mul_f32_e32 v17, 0xbfb8aa3b, v17
	v_exp_f32_e32 v17, v17
	v_lshlrev_b32_e32 v16, 16, v16
	v_mul_f32_e32 v16, 0xbfb8aa3b, v16
	s_waitcnt lgkmcnt(5)
	v_lshlrev_b32_e32 v18, 16, v18
	v_exp_f32_e32 v16, v16
	v_add_f32_e32 v17, 1.0, v17
	v_mul_f32_e32 v18, 0xbfb8aa3b, v18
	v_rcp_f32_e32 v17, v17
	v_exp_f32_e32 v18, v18
	v_add_f32_e32 v16, 1.0, v16
	v_rcp_f32_e32 v16, v16
	v_fma_f32 v33, v163, v17, v162
	v_add_f32_e32 v17, 1.0, v18
	s_waitcnt lgkmcnt(4)
	v_lshlrev_b32_e32 v18, 16, v19
	v_mul_f32_e32 v18, 0xbfb8aa3b, v18
	v_rcp_f32_e32 v17, v17
	v_exp_f32_e32 v18, v18
	v_fma_f32 v32, v163, v16, v162
	v_log_f32_e32 v16, v32
	v_log_f32_e32 v19, v33
	v_fma_f32 v34, v163, v17, v162
	v_add_f32_e32 v18, 1.0, v18
	v_log_f32_e32 v17, v34
	v_rcp_f32_e32 v18, v18
	v_add_f32_e32 v31, 0, v16
	v_add_f32_e32 v30, v31, v19
	v_add_f32_e32 v29, v30, v17
	v_fma_f32 v37, v163, v18, v162
	s_waitcnt lgkmcnt(3)
	v_lshlrev_b32_e32 v17, 16, v20
	s_waitcnt lgkmcnt(2)
	v_lshlrev_b32_e32 v18, 16, v21
	v_mul_f32_e32 v17, 0xbfb8aa3b, v17
	v_mul_f32_e32 v18, 0xbfb8aa3b, v18
	v_log_f32_e32 v16, v37
	v_exp_f32_e32 v17, v17
	v_exp_f32_e32 v18, v18
	ds_read_u16 v57, v100
	ds_read_u16 v55, v100 offset:144
	ds_read_u16 v54, v100 offset:288
	ds_read_u16 v52, v100 offset:432
	ds_read_u16 v50, v100 offset:576
	ds_read_u16 v49, v100 offset:720
	ds_read_u16 v47, v100 offset:864
	ds_read_u16 v45, v100 offset:1008
	v_add_f32_e32 v27, v29, v16
	v_add_f32_e32 v16, 1.0, v17
	v_add_f32_e32 v17, 1.0, v18
	s_waitcnt lgkmcnt(9)
	v_lshlrev_b32_e32 v18, 16, v22
	v_mul_f32_e32 v18, 0xbfb8aa3b, v18
	v_rcp_f32_e32 v17, v17
	v_exp_f32_e32 v18, v18
	v_rcp_f32_e32 v16, v16
	v_fma_f32 v39, v163, v17, v162
	v_add_f32_e32 v17, 1.0, v18
	s_waitcnt lgkmcnt(8)
	v_lshlrev_b32_e32 v18, 16, v23
	v_mul_f32_e32 v18, 0xbfb8aa3b, v18
	v_exp_f32_e32 v18, v18
	v_rcp_f32_e32 v17, v17
	v_fma_f32 v38, v163, v16, v162
	v_log_f32_e32 v16, v38
	v_add_f32_e32 v18, 1.0, v18
	v_rcp_f32_e32 v18, v18
	v_log_f32_e32 v19, v39
	v_fma_f32 v40, v163, v17, v162
	v_log_f32_e32 v17, v40
	v_fma_f32 v41, v163, v18, v162
	v_add_f32_e32 v28, v27, v16
	v_log_f32_e32 v16, v41
	v_add_f32_e32 v26, v28, v19
	v_add_f32_e32 v25, v26, v17
	v_add_f32_e32 v24, v25, v16
	ds_write_b32 v107, v24
	ds_read_u16 v35, v153 offset:18432
	ds_read_u16 v36, v153 offset:18704
	ds_read_u16 v43, v153 offset:18976
	ds_read_u16 v44, v153 offset:19248
	ds_read_u16 v46, v153 offset:19520
	ds_read_u16 v48, v153 offset:19792
	ds_read_u16 v51, v153 offset:20064
	ds_read_u16 v53, v153 offset:20336
	ds_read_u16 v56, v153 offset:20608
	ds_read_u16 v58, v153 offset:20880
	ds_read_u16 v59, v153 offset:21152
	ds_read_u16 v60, v153 offset:21424
	ds_read_u16 v61, v153 offset:21696
	ds_read_u16 v62, v153 offset:21968
	ds_read_u16 v63, v153 offset:22240
	ds_read_u16 v64, v153 offset:22512
	s_waitcnt lgkmcnt(0)
	s_barrier
	ds_read2st64_b32 v[20:21], v108 offset0:2 offset1:3
	ds_read2st64_b32 v[18:19], v108 offset0:4 offset1:5
	ds_read2st64_b32 v[16:17], v108 offset0:6 offset1:7
	ds_read2st64_b32 v[22:23], v108 offset1:1
	s_waitcnt lgkmcnt(3)
	v_add_f32_e32 v42, v20, v21
	s_waitcnt lgkmcnt(2)
	v_add_f32_e32 v65, v18, v19
	s_waitcnt lgkmcnt(1)
	v_add_f32_e32 v17, v16, v17
	v_add_f32_e32 v17, v65, v17
	s_waitcnt lgkmcnt(0)
	v_add_f32_e32 v65, v22, v23
	v_add_f32_e32 v42, v65, v42
	v_add_f32_e32 v17, v42, v17
	v_exp_f32_e32 v17, v17
	s_and_saveexec_b64 s[26:27], s[42:43]
	ds_write_b32 v109, v17
	s_or_b64 exec, exec, s[26:27]
	v_add_f32_e32 v22, 0, v22
	v_cndmask_b32_e64 v22, 0, v22, s[64:65]
	v_cndmask_b32_e64 v23, 0, v23, s[66:67]
	v_add_f32_e32 v22, v22, v23
	v_cndmask_b32_e64 v20, 0, v20, s[68:69]
	v_add_f32_e32 v20, v22, v20
	v_cndmask_b32_e64 v21, 0, v21, s[70:71]
	v_add_f32_e32 v20, v20, v21
	v_cndmask_b32_e64 v18, 0, v18, s[72:73]
	v_add_f32_e32 v18, v20, v18
	v_cndmask_b32_e64 v19, 0, v19, s[74:75]
	v_add_f32_e32 v18, v18, v19
	v_cndmask_b32_e64 v16, 0, v16, s[76:77]
	v_add_f32_e32 v16, v18, v16
	v_max_f32_e64 v18, -v42, -v42
	v_min_f32_e32 v18, 0x42f00000, v18
	v_exp_f32_e32 v21, v18
	v_add_f32_e32 v18, v31, v16
	v_exp_f32_e32 v19, v18
	v_min_f32_e64 v18, -v18, s33
	v_exp_f32_e32 v22, v42
	v_exp_f32_e32 v18, v18
	v_lshlrev_b32_e32 v57, 16, v57
	v_mul_f32_e32 v20, v21, v19
	v_sub_f32_e32 v32, 1.0, v32
	v_mul_f32_e32 v23, v22, v18
	v_mul_f32_e32 v18, v17, v18
	v_min_f32_e32 v20, 0x5affcb9e, v20
	v_min_f32_e32 v18, 1.0, v18
	v_mul_f32_e32 v19, v19, v57
	v_min_f32_e32 v23, 0x5affcb9e, v23
	v_mul_f32_e32 v20, v20, v57
	v_cvt_pk_bf16_f32 v19, v19, v20
	v_mul_f32_e32 v18, v32, v18
	v_mul_f32_e32 v20, v32, v23
	v_cvt_pk_bf16_f32 v18, v20, v18
	ds_write_b16 v181, v19
	ds_write_b16_d16_hi v181, v19 offset:9216
	ds_write_b16 v181, v18 offset:18432
	v_add_f32_e32 v19, v30, v16
	v_exp_f32_e32 v20, v19
	v_min_f32_e64 v19, -v19, s33
	v_exp_f32_e32 v19, v19
	v_lshlrev_b32_e32 v55, 16, v55
	v_mul_f32_e32 v23, v21, v20
	v_sub_f32_e32 v33, 1.0, v33
	v_mul_f32_e32 v30, v22, v19
	v_mul_f32_e32 v19, v17, v19
	v_min_f32_e32 v23, 0x5affcb9e, v23
	v_min_f32_e32 v19, 1.0, v19
	v_mul_f32_e32 v20, v20, v55
	v_min_f32_e32 v30, 0x5affcb9e, v30
; #define GAS __attribute__((address_space(1)))
; __device__ __forceinline__ unsigned cvtpk(float lo, float hi) { unsigned r; asm volatile("v_cvt_pk_bf16_f32 %0, %1, %2" : "=v"(r) : "v"(lo), "v"(hi)); return r; }
; __device__ __forceinline__ void hgrn_phase(const Params& p, int e, char* lds) {
;     ...
;         unsigned ksw[4];
; #pragma unroll
;         for (int i = 0; i < 8; ++i) { const float cc = off + cl[i];
;           const float e1 = __builtin_amdgcn_exp2f(cc), inv1 = __builtin_amdgcn_exp2f(fminf(-cc, 120.f));
;           const float ea = fminf(e1 * em, 3.6e16f), eb = fminf(inv1 * emi, 3.6e16f), es = fminf(inv1 * el, 1.0f);
;           const int t = 8 * rq + i;
;           const unsigned w0 = cvtpk(qf[i] * e1, qf[i] * ea), w1 = cvtpk(kk[i] * eb, kk[i] * es);
;           *(unsigned short*)(QD + t * PK + k * 2) = (unsigned short)(w0 & 0xffffu);
;           *(unsigned short*)(QA + t * PK + k * 2) = (unsigned short)(w0 >> 16);
;           *(unsigned short*)(KB + t * PK + k * 2) = (unsigned short)(w1 & 0xffffu);
;           if (i & 1) ksw[i >> 1] |= (w1 & 0xffff0000u); else ksw[i >> 1] = (w1 >> 16); }
;         *(u32x4*)(KS + k * PJ + rq * 16) = (u32x4){ksw[0], ksw[1], ksw[2], ksw[3]};
;         *(u32x4*)(VT + vv * PJ + jg * 32) = vpa; *(u32x4*)(VT + vv * PJ + jg * 32 + 16) = vpb; }
;       LBAR();
;       if (c + 1 < SEQ / 64) { const int bc = base0 + rsb * 64 * (c + 1); const int o0 = bc + rsb * lr;
;         gq = *(const GAS u32x4*)(bigc + (size_t)(unsigned)(o0 + qcol)); gz = *(const GAS u32x4*)(bigc + (size_t)(unsigned)(o0 + zcol));
;         gv0 = *(const GAS u32x4*)(bigc + (size_t)(unsigned)(bc + rsb * vr + vcol)); gv1 = *(const GAS u32x4*)(bigc + (size_t)(unsigned)(bc + rsb * (vr + 32) + vcol)); }
;     ...
;       f32x4 oacc[4];
;       const int wq = wave >> 1, vt0 = 4 * (wave & 1);
;       { const int ttA = 2 * (wave & 1); const char* STp = ST + pb * (128 * PK);
;         bf16x8 fa[2], fb0[2], fb1[2], fqd[2], fs[4][2];
; #pragma unroll
;         for (int ks = 0; ks < 2; ++ks) { fa[ks] = ldfrag(KB, 16 * wq + fr, PK, ks * 32 + fq_ * 8); fb0[ks] = ldfrag(QA, 16 * ttA + fr, PK, ks * 32 + fq_ * 8); fb1[ks] = ldfrag(QA, 16 * (ttA + 1) + fr, PK, ks * 32 + fq_ * 8);
;           fqd[ks] = ldfrag(QD, 16 * wq + fr, PK, ks * 32 + fq_ * 8);
; #pragma unroll
;           for (int n = 0; n < 4; ++n) fs[n][ks] = ldfrag(STp, 16 * (vt0 + n) + fr, PK, ks * 32 + fq_ * 8); }
	v_mul_f32_e32 v23, v23, v55
	v_cvt_pk_bf16_f32 v20, v20, v23
	v_mul_f32_e32 v19, v33, v19
	v_mul_f32_e32 v23, v33, v30
	v_cvt_pk_bf16_f32 v19, v23, v19
	ds_write_b16 v181, v20 offset:144
	ds_write_b16_d16_hi v181, v20 offset:9360
	ds_write_b16 v181, v19 offset:18576
	v_add_f32_e32 v20, v29, v16
	v_exp_f32_e32 v23, v20
	v_min_f32_e64 v20, -v20, s33
	v_exp_f32_e32 v20, v20
	v_lshrrev_b32_e32 v18, 16, v18
	v_and_or_b32 v18, v19, s13, v18
	v_mul_f32_e32 v19, v21, v23
	v_lshlrev_b32_e32 v54, 16, v54
	v_min_f32_e32 v19, 0x5affcb9e, v19
	v_mul_f32_e32 v29, v22, v20
	v_mul_f32_e32 v20, v17, v20
	v_sub_f32_e32 v34, 1.0, v34
	v_min_f32_e32 v20, 1.0, v20
	v_mul_f32_e32 v19, v19, v54
	v_min_f32_e32 v29, 0x5affcb9e, v29
	v_mul_f32_e32 v23, v23, v54
	v_cvt_pk_bf16_f32 v19, v23, v19
	v_mul_f32_e32 v20, v34, v20
	v_mul_f32_e32 v23, v34, v29
	v_cvt_pk_bf16_f32 v20, v23, v20
	ds_write_b16 v181, v19 offset:288
	ds_write_b16_d16_hi v181, v19 offset:9504
	ds_write_b16 v181, v20 offset:18720
	v_add_f32_e32 v19, v27, v16
	v_exp_f32_e32 v23, v19
	v_min_f32_e64 v19, -v19, s33
	v_exp_f32_e32 v19, v19
	v_lshlrev_b32_e32 v52, 16, v52
	v_mul_f32_e32 v27, v21, v23
	v_sub_f32_e32 v37, 1.0, v37
	v_mul_f32_e32 v29, v22, v19
	v_mul_f32_e32 v19, v17, v19
	v_min_f32_e32 v27, 0x5affcb9e, v27
	v_min_f32_e32 v19, 1.0, v19
	v_mul_f32_e32 v23, v23, v52
	v_min_f32_e32 v29, 0x5affcb9e, v29
	v_mul_f32_e32 v27, v27, v52
	v_cvt_pk_bf16_f32 v23, v23, v27
	v_mul_f32_e32 v19, v37, v19
	v_mul_f32_e32 v27, v37, v29
	v_cvt_pk_bf16_f32 v19, v27, v19
	ds_write_b16 v181, v23 offset:432
	ds_write_b16_d16_hi v181, v23 offset:9648
	ds_write_b16 v181, v19 offset:18864
	v_add_f32_e32 v23, v28, v16
	v_exp_f32_e32 v27, v23
	v_min_f32_e64 v23, -v23, s33
	v_exp_f32_e32 v23, v23
	v_lshrrev_b32_e32 v20, 16, v20
	v_and_or_b32 v19, v19, s13, v20
	v_mul_f32_e32 v20, v21, v27
	v_lshlrev_b32_e32 v50, 16, v50
	v_min_f32_e32 v20, 0x5affcb9e, v20
	v_mul_f32_e32 v28, v22, v23
	v_mul_f32_e32 v23, v17, v23
	v_sub_f32_e32 v65, 1.0, v38
	v_min_f32_e32 v23, 1.0, v23
	v_mul_f32_e32 v20, v20, v50
	v_min_f32_e32 v28, 0x5affcb9e, v28
	v_mul_f32_e32 v27, v27, v50
	v_cvt_pk_bf16_f32 v20, v27, v20
	v_mul_f32_e32 v23, v65, v23
	v_mul_f32_e32 v27, v65, v28
	v_cvt_pk_bf16_f32 v23, v27, v23
	ds_write_b16 v182, v20 offset:576
	ds_write_b16_d16_hi v182, v20 offset:9792
	ds_write_b16 v182, v23 offset:19008
	v_add_f32_e32 v20, v26, v16
	v_exp_f32_e32 v26, v20
	v_min_f32_e64 v20, -v20, s33
	v_exp_f32_e32 v20, v20
	v_lshlrev_b32_e32 v49, 16, v49
	v_mul_f32_e32 v27, v21, v26
	v_sub_f32_e32 v66, 1.0, v39
	v_mul_f32_e32 v28, v22, v20
	v_mul_f32_e32 v20, v17, v20
	v_min_f32_e32 v27, 0x5affcb9e, v27
	v_min_f32_e32 v20, 1.0, v20
	v_mul_f32_e32 v26, v26, v49
	v_min_f32_e32 v28, 0x5affcb9e, v28
	v_mul_f32_e32 v27, v27, v49
	v_cvt_pk_bf16_f32 v26, v26, v27
	v_mul_f32_e32 v20, v66, v20
	v_add_f32_e32 v25, v25, v16
	v_mul_f32_e32 v27, v66, v28
	v_cvt_pk_bf16_f32 v20, v27, v20
	ds_write_b16 v182, v26 offset:720
	ds_write_b16_d16_hi v182, v26 offset:9936
	ds_write_b16 v182, v20 offset:19152
	v_exp_f32_e32 v26, v25
	v_min_f32_e64 v25, -v25, s33
	v_exp_f32_e32 v25, v25
	v_lshrrev_b32_e32 v23, 16, v23
	v_and_or_b32 v20, v20, s13, v23
	v_mul_f32_e32 v23, v21, v26
	v_lshlrev_b32_e32 v67, 16, v47
	v_min_f32_e32 v23, 0x5affcb9e, v23
	v_mul_f32_e32 v27, v22, v25
	v_mul_f32_e32 v25, v17, v25
	v_sub_f32_e32 v68, 1.0, v40
	v_min_f32_e32 v25, 1.0, v25
	v_mul_f32_e32 v23, v23, v67
	v_min_f32_e32 v27, 0x5affcb9e, v27
	v_mul_f32_e32 v26, v26, v67
	v_cvt_pk_bf16_f32 v23, v26, v23
	v_mul_f32_e32 v25, v68, v25
	v_add_f32_e32 v16, v24, v16
	v_mul_f32_e32 v26, v68, v27
	v_cvt_pk_bf16_f32 v25, v26, v25
	ds_write_b16 v182, v23 offset:864
	ds_write_b16_d16_hi v182, v23 offset:10080
	ds_write_b16 v182, v25 offset:19296
	v_exp_f32_e32 v23, v16
	v_min_f32_e64 v16, -v16, s33
	v_exp_f32_e32 v16, v16
	v_lshlrev_b32_e32 v69, 16, v45
	v_mul_f32_e32 v21, v21, v23
	v_min_f32_e32 v21, 0x5affcb9e, v21
	v_mul_f32_e32 v22, v22, v16
	v_mul_f32_e32 v16, v17, v16
	v_sub_f32_e32 v70, 1.0, v41
	v_min_f32_e32 v22, 0x5affcb9e, v22
	v_min_f32_e32 v16, 1.0, v16
	v_mul_f32_e32 v17, v23, v69
	v_mul_f32_e32 v21, v21, v69
	v_lshrrev_b32_e32 v24, 16, v25
	v_cvt_pk_bf16_f32 v17, v17, v21
	v_mul_f32_e32 v21, v70, v22
	v_mul_f32_e32 v16, v70, v16
	v_cvt_pk_bf16_f32 v16, v21, v16
	v_perm_b32 v41, v64, v63, s7
	v_and_or_b32 v21, v16, s13, v24
	v_perm_b32 v40, v62, v61, s7
	v_perm_b32 v39, v60, v59, s7
	v_perm_b32 v38, v58, v56, s7
	v_perm_b32 v47, v53, v51, s7
	v_perm_b32 v46, v48, v46, s7
	v_perm_b32 v45, v44, v43, s7
	v_perm_b32 v44, v36, v35, s7
	ds_write_b16 v182, v17 offset:1008
	ds_write_b16_d16_hi v182, v17 offset:10224
	ds_write_b16 v182, v16 offset:19440
	ds_write_b128 v154, v[18:21] offset:27648
	ds_write_b128 v155, v[44:47] offset:36864
	ds_write_b128 v183, v[38:41] offset:36880
	s_waitcnt lgkmcnt(0)
	s_barrier
	v_add_u32_e32 v16, s8, v172
	v_add_u32_e32 v20, v171, v170
	v_add_u32_e32 v24, vcc_hi, v169
	v_add_u32_e32 v28, vcc_hi, v168
	global_load_dwordx4 v[16:19], v16, s[30:31]
	s_nop 0
	global_load_dwordx4 v[20:23], v20, s[30:31]
	s_nop 0
	global_load_dwordx4 v[24:27], v24, s[30:31]
	s_nop 0
	global_load_dwordx4 v[28:31], v28, s[30:31]
	s_and_b32 s14, vcc_lo, 1
	s_mul_i32 s5, s14, 0x4800
	v_add_u32_e32 v32, s5, v122
	v_add_u32_e32 v36, v32, v101
	v_add_u32_e32 v37, v32, v119
	v_add_u32_e32 v38, v32, v120
	v_add_u32_e32 v39, v32, v121
	v_add_u32_e32 v173, v111, v110
	ds_read_b128 v[76:79], v156 offset:18432
	ds_read_b128 v[56:59], v156 offset:18496
	ds_read_b128 v[52:55], v173 offset:9216
	ds_read_b128 v[68:71], v173 offset:9280
	ds_read_b128 v[84:87], v173 offset:11520
	ds_read_b128 v[64:67], v173 offset:11584
	ds_read_b128 v[72:75], v156
	ds_read_b128 v[32:35], v156 offset:64
	ds_read_b128 v[80:83], v36 offset:64512
	ds_read_b128 v[48:51], v36 offset:64576
	ds_read_b128 v[88:91], v37 offset:64512
	ds_read_b128 v[44:47], v37 offset:64576
	ds_read_b128 v[92:95], v38 offset:64512
	ds_read_b128 v[40:43], v38 offset:64576
	ds_read_b128 v[96:99], v39 offset:64512
	ds_read_b128 v[36:39], v39 offset:64576
	s_waitcnt lgkmcnt(0)
	v_mov_b32_e32 v145, v144
	v_mov_b32_e32 v146, v144
	v_mov_b32_e32 v147, v144
	v_mov_b64_e32 v[60:61], v[144:145]
	v_mov_b64_e32 v[62:63], v[146:147]
	s_and_saveexec_b64 s[26:27], s[44:45]
	s_cbranch_execz .LBB0_226
	s_waitcnt lgkmcnt(13)
	v_mfma_f32_16x16x32_bf16 v[60:63], v[76:79], v[52:55], 0

; __device__ __forceinline__ float bf2f(unsigned short b) { return __uint_as_float(((unsigned)b) << 16); }
; #define LBAR() do { asm volatile("s_waitcnt lgkmcnt(0)" ::: "memory"); __builtin_amdgcn_s_barrier(); asm volatile("" ::: "memory"); } while (0)
; __device__ __forceinline__ void hgrn_phase(const Params& p, int e, char* lds) {
;     ...
;       *(u32x4*)(RQ + lr * PK + lc8 * 2) = gq; *(u32x4*)(RZ + lr * PK + lc8 * 2) = gz;
;       *(u32x4*)(RV + vr * PV + vc8 * 2) = gv0; *(u32x4*)(RV + (vr + 32) * PV + vc8 * 2) = gv1;
;       LBAR();
;       float qf[8], kk[8], cl[8]; float run = 0.f;
; #pragma unroll
;       for (int i = 0; i < 8; ++i) { const int t = 8 * rq + i; const float z = bf2f(*(const unsigned short*)(RZ + t * PK + k * 2)); qf[i] = bf2f(*(const unsigned short*)(RQ + t * PK + k * 2));
;         const float sg = __builtin_amdgcn_rcpf(1.0f + __builtin_amdgcn_exp2f(-L2E * z)); const float f = lbk + (1.0f - lbk) * sg;
;         run += __builtin_amdgcn_logf(f); cl[i] = run; kk[i] = 1.0f - f; }
;       TOT[rq * 64 + k] = run;
;       unsigned short rvv[16];
; #pragma unroll
;       for (int i = 0; i < 16; ++i) rvv[i] = *(const unsigned short*)(RV + (16 * jg + i) * PV + vv * 2);
;       u32x4 vpa, vpb;
;       vpa.x = rvv[0] | ((unsigned)rvv[1] << 16); vpa.y = rvv[2] | ((unsigned)rvv[3] << 16); vpa.z = rvv[4] | ((unsigned)rvv[5] << 16); vpa.w = rvv[6] | ((unsigned)rvv[7] << 16);
;       vpb.x = rvv[8] | ((unsigned)rvv[9] << 16); vpb.y = rvv[10] | ((unsigned)rvv[11] << 16); vpb.z = rvv[12] | ((unsigned)rvv[13] << 16); vpb.w = rvv[14] | ((unsigned)rvv[15] << 16);
;       LBAR();
;       { float tt[8];
; #pragma unroll
;         for (int r8 = 0; r8 < 8; ++r8) tt[r8] = TOT[r8 * 64 + k];
;         const float mid = (tt[0] + tt[1]) + (tt[2] + tt[3]), last = mid + ((tt[4] + tt[5]) + (tt[6] + tt[7]));
;         float off = 0.f;
; #pragma unroll
;         for (int r8 = 0; r8 < 7; ++r8) off += (r8 < rq) ? tt[r8] : 0.f;
;         const float el = __builtin_amdgcn_exp2f(last), em = __builtin_amdgcn_exp2f(fminf(-mid, 120.f)), emi = __builtin_amdgcn_exp2f(mid);
;         if (rq == 0) DD[k] = el;
.LBB0_232:
	s_waitcnt vmcnt(19)
	ds_write_b128 v143, v[16:19]
	s_waitcnt vmcnt(18)
	ds_write_b128 v143, v[20:23] offset:9216
	s_waitcnt vmcnt(17)
	ds_write_b128 v152, v[24:27] offset:18432
	s_waitcnt vmcnt(16)
	ds_write_b128 v152, v[28:31] offset:27136
	s_waitcnt lgkmcnt(0)
	s_barrier
	ds_read_u16 v16, v100 offset:9216
	ds_read_u16 v17, v100 offset:9360
	ds_read_u16 v18, v100 offset:9504
	ds_read_u16 v19, v100 offset:9648
	ds_read_u16 v20, v100 offset:9792
	ds_read_u16 v21, v100 offset:9936
	ds_read_u16 v22, v100 offset:10080
	ds_read_u16 v23, v100 offset:10224
	s_waitcnt lgkmcnt(6)
	v_lshlrev_b32_e32 v17, 16, v17
	v_mul_f32_e32 v17, 0xbfb8aa3b, v17
	v_exp_f32_e32 v17, v17
	v_lshlrev_b32_e32 v16, 16, v16
	v_mul_f32_e32 v16, 0xbfb8aa3b, v16
	s_waitcnt lgkmcnt(5)
	v_lshlrev_b32_e32 v18, 16, v18
	v_exp_f32_e32 v16, v16
	v_add_f32_e32 v17, 1.0, v17
	v_mul_f32_e32 v18, 0xbfb8aa3b, v18
	v_rcp_f32_e32 v17, v17
	v_exp_f32_e32 v18, v18
	v_add_f32_e32 v16, 1.0, v16
	v_rcp_f32_e32 v16, v16
	v_fma_f32 v33, v163, v17, v162
	v_add_f32_e32 v17, 1.0, v18
	s_waitcnt lgkmcnt(4)
	v_lshlrev_b32_e32 v18, 16, v19
	v_mul_f32_e32 v18, 0xbfb8aa3b, v18
	v_rcp_f32_e32 v17, v17
	v_exp_f32_e32 v18, v18
	v_fma_f32 v32, v163, v16, v162
	v_log_f32_e32 v16, v32
	v_log_f32_e32 v19, v33
	v_fma_f32 v34, v163, v17, v162
	v_add_f32_e32 v18, 1.0, v18
	v_log_f32_e32 v17, v34
	v_rcp_f32_e32 v18, v18
	v_add_f32_e32 v31, 0, v16
	v_add_f32_e32 v30, v31, v19
	v_add_f32_e32 v29, v30, v17
	v_fma_f32 v36, v163, v18, v162
	s_waitcnt lgkmcnt(3)
	v_lshlrev_b32_e32 v17, 16, v20
	s_waitcnt lgkmcnt(2)
	v_lshlrev_b32_e32 v18, 16, v21
	v_mul_f32_e32 v17, 0xbfb8aa3b, v17
	v_mul_f32_e32 v18, 0xbfb8aa3b, v18
	v_log_f32_e32 v16, v36
	v_exp_f32_e32 v17, v17
	v_exp_f32_e32 v18, v18
	ds_read_u16 v56, v100
	ds_read_u16 v54, v100 offset:144
	ds_read_u16 v53, v100 offset:288
	ds_read_u16 v51, v100 offset:432
	ds_read_u16 v49, v100 offset:576
	ds_read_u16 v48, v100 offset:720
	ds_read_u16 v46, v100 offset:864
	ds_read_u16 v44, v100 offset:1008
	v_add_f32_e32 v27, v29, v16
	v_add_f32_e32 v16, 1.0, v17
	v_add_f32_e32 v17, 1.0, v18
	s_waitcnt lgkmcnt(9)
	v_lshlrev_b32_e32 v18, 16, v22
	v_mul_f32_e32 v18, 0xbfb8aa3b, v18
	v_rcp_f32_e32 v17, v17
	v_exp_f32_e32 v18, v18
	v_rcp_f32_e32 v16, v16
	v_fma_f32 v39, v163, v17, v162
	v_add_f32_e32 v17, 1.0, v18
	s_waitcnt lgkmcnt(8)
	v_lshlrev_b32_e32 v18, 16, v23
	v_mul_f32_e32 v18, 0xbfb8aa3b, v18
	v_exp_f32_e32 v18, v18
	v_rcp_f32_e32 v17, v17
	v_fma_f32 v38, v163, v16, v162
	v_log_f32_e32 v16, v38
	v_add_f32_e32 v18, 1.0, v18
	v_rcp_f32_e32 v18, v18
	v_log_f32_e32 v19, v39
	v_fma_f32 v40, v163, v17, v162
	v_log_f32_e32 v17, v40
	v_fmac_f32_e32 v162, v163, v18
	v_add_f32_e32 v28, v27, v16
	v_log_f32_e32 v16, v162
	v_add_f32_e32 v26, v28, v19
	v_add_f32_e32 v25, v26, v17
	v_add_f32_e32 v24, v25, v16
	ds_write_b32 v107, v24
	ds_read_u16 v35, v153 offset:18432
	ds_read_u16 v37, v153 offset:18704
	ds_read_u16 v41, v153 offset:18976
	ds_read_u16 v43, v153 offset:19248
	ds_read_u16 v45, v153 offset:19520
	ds_read_u16 v47, v153 offset:19792
	ds_read_u16 v50, v153 offset:20064
	ds_read_u16 v52, v153 offset:20336
	ds_read_u16 v55, v153 offset:20608
	ds_read_u16 v57, v153 offset:20880
	ds_read_u16 v58, v153 offset:21152
	ds_read_u16 v59, v153 offset:21424
	ds_read_u16 v60, v153 offset:21696
	ds_read_u16 v61, v153 offset:21968
	ds_read_u16 v62, v153 offset:22240
	ds_read_u16 v63, v153 offset:22512
	s_waitcnt lgkmcnt(0)
	s_barrier
	ds_read2st64_b32 v[20:21], v108 offset0:2 offset1:3
	ds_read2st64_b32 v[18:19], v108 offset0:4 offset1:5
	ds_read2st64_b32 v[16:17], v108 offset0:6 offset1:7
	ds_read2st64_b32 v[22:23], v108 offset1:1
	s_waitcnt lgkmcnt(3)
	v_add_f32_e32 v42, v20, v21
	s_waitcnt lgkmcnt(2)
	v_add_f32_e32 v64, v18, v19
	s_waitcnt lgkmcnt(1)
	v_add_f32_e32 v17, v16, v17
	v_add_f32_e32 v17, v64, v17
	s_waitcnt lgkmcnt(0)
	v_add_f32_e32 v64, v22, v23
	v_add_f32_e32 v42, v64, v42
	v_add_f32_e32 v17, v42, v17
	v_exp_f32_e32 v17, v17
	s_and_saveexec_b64 s[26:27], s[42:43]
	ds_write_b32 v109, v17
	s_or_b64 exec, exec, s[26:27]
	v_add_f32_e32 v22, 0, v22
	v_cndmask_b32_e64 v22, 0, v22, s[64:65]
	v_cndmask_b32_e64 v23, 0, v23, s[66:67]
	v_add_f32_e32 v22, v22, v23
	v_cndmask_b32_e64 v20, 0, v20, s[68:69]
	v_add_f32_e32 v20, v22, v20
	v_cndmask_b32_e64 v21, 0, v21, s[70:71]
	v_add_f32_e32 v20, v20, v21
	v_cndmask_b32_e64 v18, 0, v18, s[72:73]
	v_add_f32_e32 v18, v20, v18
	v_cndmask_b32_e64 v19, 0, v19, s[74:75]
	v_add_f32_e32 v18, v18, v19
	v_cndmask_b32_e64 v16, 0, v16, s[76:77]
	v_add_f32_e32 v16, v18, v16
	v_max_f32_e64 v18, -v42, -v42
	v_min_f32_e32 v18, 0x42f00000, v18
	v_exp_f32_e32 v21, v18
	v_add_f32_e32 v18, v31, v16
	v_exp_f32_e32 v19, v18
	v_min_f32_e64 v18, -v18, s33
	v_exp_f32_e32 v22, v42
	v_exp_f32_e32 v18, v18
	v_lshlrev_b32_e32 v56, 16, v56
	v_mul_f32_e32 v20, v21, v19
	v_sub_f32_e32 v32, 1.0, v32
	v_mul_f32_e32 v23, v22, v18
	v_mul_f32_e32 v18, v17, v18
	v_min_f32_e32 v20, 0x5affcb9e, v20
	v_min_f32_e32 v18, 1.0, v18
	v_mul_f32_e32 v19, v19, v56
	v_min_f32_e32 v23, 0x5affcb9e, v23
	v_mul_f32_e32 v20, v20, v56
	v_cvt_pk_bf16_f32 v19, v19, v20
	v_mul_f32_e32 v18, v32, v18
	v_mul_f32_e32 v20, v32, v23
	v_cvt_pk_bf16_f32 v18, v20, v18
	ds_write_b16 v181, v19
	ds_write_b16_d16_hi v181, v19 offset:9216
	ds_write_b16 v181, v18 offset:18432
	v_add_f32_e32 v19, v30, v16
	v_exp_f32_e32 v20, v19
	v_min_f32_e64 v19, -v19, s33
	v_exp_f32_e32 v19, v19
	v_lshlrev_b32_e32 v54, 16, v54
	v_mul_f32_e32 v23, v21, v20
	v_sub_f32_e32 v33, 1.0, v33
	v_mul_f32_e32 v30, v22, v19
	v_mul_f32_e32 v19, v17, v19
	v_min_f32_e32 v23, 0x5affcb9e, v23
	v_min_f32_e32 v19, 1.0, v19
; #define GAS __attribute__((address_space(1)))
; __device__ __forceinline__ unsigned cvtpk(float lo, float hi) { unsigned r; asm volatile("v_cvt_pk_bf16_f32 %0, %1, %2" : "=v"(r) : "v"(lo), "v"(hi)); return r; }
; __device__ __forceinline__ void hgrn_phase(const Params& p, int e, char* lds) {
;     ...
;         unsigned ksw[4];
; #pragma unroll
;         for (int i = 0; i < 8; ++i) { const float cc = off + cl[i];
;           const float e1 = __builtin_amdgcn_exp2f(cc), inv1 = __builtin_amdgcn_exp2f(fminf(-cc, 120.f));
;           const float ea = fminf(e1 * em, 3.6e16f), eb = fminf(inv1 * emi, 3.6e16f), es = fminf(inv1 * el, 1.0f);
;           const int t = 8 * rq + i;
;           const unsigned w0 = cvtpk(qf[i] * e1, qf[i] * ea), w1 = cvtpk(kk[i] * eb, kk[i] * es);
;           *(unsigned short*)(QD + t * PK + k * 2) = (unsigned short)(w0 & 0xffffu);
;           *(unsigned short*)(QA + t * PK + k * 2) = (unsigned short)(w0 >> 16);
;           *(unsigned short*)(KB + t * PK + k * 2) = (unsigned short)(w1 & 0xffffu);
;           if (i & 1) ksw[i >> 1] |= (w1 & 0xffff0000u); else ksw[i >> 1] = (w1 >> 16); }
;         *(u32x4*)(KS + k * PJ + rq * 16) = (u32x4){ksw[0], ksw[1], ksw[2], ksw[3]};
;         *(u32x4*)(VT + vv * PJ + jg * 32) = vpa; *(u32x4*)(VT + vv * PJ + jg * 32 + 16) = vpb; }
;       LBAR();
;       if (c + 1 < SEQ / 64) { const int bc = base0 + rsb * 64 * (c + 1); const int o0 = bc + rsb * lr;
;         gq = *(const GAS u32x4*)(bigc + (size_t)(unsigned)(o0 + qcol)); gz = *(const GAS u32x4*)(bigc + (size_t)(unsigned)(o0 + zcol));
;         gv0 = *(const GAS u32x4*)(bigc + (size_t)(unsigned)(bc + rsb * vr + vcol)); gv1 = *(const GAS u32x4*)(bigc + (size_t)(unsigned)(bc + rsb * (vr + 32) + vcol)); }
;     ...
;       f32x4 oacc[4];
;       const int wq = wave >> 1, vt0 = 4 * (wave & 1);
;       { const int ttA = 2 * (wave & 1); const char* STp = ST + pb * (128 * PK);
;         bf16x8 fa[2], fb0[2], fb1[2], fqd[2], fs[4][2];
; #pragma unroll
;         for (int ks = 0; ks < 2; ++ks) { fa[ks] = ldfrag(KB, 16 * wq + fr, PK, ks * 32 + fq_ * 8); fb0[ks] = ldfrag(QA, 16 * ttA + fr, PK, ks * 32 + fq_ * 8); fb1[ks] = ldfrag(QA, 16 * (ttA + 1) + fr, PK, ks * 32 + fq_ * 8);
;           fqd[ks] = ldfrag(QD, 16 * wq + fr, PK, ks * 32 + fq_ * 8);
; #pragma unroll
;           for (int n = 0; n < 4; ++n) fs[n][ks] = ldfrag(STp, 16 * (vt0 + n) + fr, PK, ks * 32 + fq_ * 8); }
	v_mul_f32_e32 v20, v20, v54
	v_min_f32_e32 v30, 0x5affcb9e, v30
	v_mul_f32_e32 v23, v23, v54
	v_cvt_pk_bf16_f32 v20, v20, v23
	v_mul_f32_e32 v19, v33, v19
	v_mul_f32_e32 v23, v33, v30
	v_cvt_pk_bf16_f32 v19, v23, v19
	ds_write_b16 v181, v20 offset:144
	ds_write_b16_d16_hi v181, v20 offset:9360
	ds_write_b16 v181, v19 offset:18576
	v_add_f32_e32 v20, v29, v16
	v_exp_f32_e32 v23, v20
	v_min_f32_e64 v20, -v20, s33
	v_exp_f32_e32 v20, v20
	v_lshrrev_b32_e32 v18, 16, v18
	v_and_or_b32 v18, v19, s13, v18
	v_mul_f32_e32 v19, v21, v23
	v_lshlrev_b32_e32 v53, 16, v53
	v_min_f32_e32 v19, 0x5affcb9e, v19
	v_mul_f32_e32 v29, v22, v20
	v_mul_f32_e32 v20, v17, v20
	v_sub_f32_e32 v34, 1.0, v34
	v_min_f32_e32 v20, 1.0, v20
	v_mul_f32_e32 v19, v19, v53
	v_min_f32_e32 v29, 0x5affcb9e, v29
	v_mul_f32_e32 v23, v23, v53
	v_cvt_pk_bf16_f32 v19, v23, v19
	v_mul_f32_e32 v20, v34, v20
	v_mul_f32_e32 v23, v34, v29
	v_cvt_pk_bf16_f32 v20, v23, v20
	ds_write_b16 v181, v19 offset:288
	ds_write_b16_d16_hi v181, v19 offset:9504
	ds_write_b16 v181, v20 offset:18720
	v_add_f32_e32 v19, v27, v16
	v_exp_f32_e32 v23, v19
	v_min_f32_e64 v19, -v19, s33
	v_exp_f32_e32 v19, v19
	v_lshlrev_b32_e32 v51, 16, v51
	v_mul_f32_e32 v27, v21, v23
	v_sub_f32_e32 v36, 1.0, v36
	v_mul_f32_e32 v29, v22, v19
	v_mul_f32_e32 v19, v17, v19
	v_min_f32_e32 v27, 0x5affcb9e, v27
	v_min_f32_e32 v19, 1.0, v19
	v_mul_f32_e32 v23, v23, v51
	v_min_f32_e32 v29, 0x5affcb9e, v29
	v_mul_f32_e32 v27, v27, v51
	v_cvt_pk_bf16_f32 v23, v23, v27
	v_mul_f32_e32 v19, v36, v19
	v_mul_f32_e32 v27, v36, v29
	v_cvt_pk_bf16_f32 v19, v27, v19
	ds_write_b16 v181, v23 offset:432
	ds_write_b16_d16_hi v181, v23 offset:9648
	ds_write_b16 v181, v19 offset:18864
	v_add_f32_e32 v23, v28, v16
	v_exp_f32_e32 v27, v23
	v_min_f32_e64 v23, -v23, s33
	v_exp_f32_e32 v23, v23
	v_lshrrev_b32_e32 v20, 16, v20
	v_and_or_b32 v19, v19, s13, v20
	v_mul_f32_e32 v20, v21, v27
	v_lshlrev_b32_e32 v64, 16, v49
	v_min_f32_e32 v20, 0x5affcb9e, v20
	v_mul_f32_e32 v28, v22, v23
	v_mul_f32_e32 v23, v17, v23
	v_sub_f32_e32 v38, 1.0, v38
	v_min_f32_e32 v23, 1.0, v23
	v_mul_f32_e32 v20, v20, v64
	v_min_f32_e32 v28, 0x5affcb9e, v28
	v_mul_f32_e32 v27, v27, v64
	v_cvt_pk_bf16_f32 v20, v27, v20
	v_mul_f32_e32 v23, v38, v23
	v_mul_f32_e32 v27, v38, v28
	v_cvt_pk_bf16_f32 v23, v27, v23
	ds_write_b16 v182, v20 offset:576
	ds_write_b16_d16_hi v182, v20 offset:9792
	ds_write_b16 v182, v23 offset:19008
	v_add_f32_e32 v20, v26, v16
	v_exp_f32_e32 v26, v20
	v_min_f32_e64 v20, -v20, s33
	v_exp_f32_e32 v20, v20
	v_lshlrev_b32_e32 v65, 16, v48
	v_mul_f32_e32 v27, v21, v26
	v_sub_f32_e32 v39, 1.0, v39
	v_mul_f32_e32 v28, v22, v20
	v_mul_f32_e32 v20, v17, v20
	v_min_f32_e32 v27, 0x5affcb9e, v27
	v_min_f32_e32 v20, 1.0, v20
	v_mul_f32_e32 v26, v26, v65
	v_min_f32_e32 v28, 0x5affcb9e, v28
	v_mul_f32_e32 v27, v27, v65
	v_cvt_pk_bf16_f32 v26, v26, v27
	v_mul_f32_e32 v20, v39, v20
	v_add_f32_e32 v25, v25, v16
	v_mul_f32_e32 v27, v39, v28
	v_cvt_pk_bf16_f32 v20, v27, v20
	ds_write_b16 v182, v26 offset:720
	ds_write_b16_d16_hi v182, v26 offset:9936
	ds_write_b16 v182, v20 offset:19152
	v_exp_f32_e32 v26, v25
	v_min_f32_e64 v25, -v25, s33
	v_exp_f32_e32 v25, v25
	v_lshrrev_b32_e32 v23, 16, v23
	v_and_or_b32 v20, v20, s13, v23
	v_mul_f32_e32 v23, v21, v26
	v_lshlrev_b32_e32 v66, 16, v46
	v_min_f32_e32 v23, 0x5affcb9e, v23
	v_mul_f32_e32 v27, v22, v25
	v_mul_f32_e32 v25, v17, v25
	v_sub_f32_e32 v40, 1.0, v40
	v_min_f32_e32 v25, 1.0, v25
	v_mul_f32_e32 v23, v23, v66
	v_min_f32_e32 v27, 0x5affcb9e, v27
	v_mul_f32_e32 v26, v26, v66
	v_cvt_pk_bf16_f32 v23, v26, v23
	v_mul_f32_e32 v25, v40, v25
	v_add_f32_e32 v16, v24, v16
	v_mul_f32_e32 v26, v40, v27
	v_cvt_pk_bf16_f32 v25, v26, v25
	ds_write_b16 v182, v23 offset:864
	ds_write_b16_d16_hi v182, v23 offset:10080
	ds_write_b16 v182, v25 offset:19296
	v_exp_f32_e32 v23, v16
	v_min_f32_e64 v16, -v16, s33
	v_exp_f32_e32 v16, v16
	v_lshlrev_b32_e32 v44, 16, v44
	v_mul_f32_e32 v21, v21, v23
	v_min_f32_e32 v21, 0x5affcb9e, v21
	v_mul_f32_e32 v22, v22, v16
	v_mul_f32_e32 v16, v17, v16
	v_sub_f32_e32 v67, 1.0, v162
	v_min_f32_e32 v22, 0x5affcb9e, v22
	v_min_f32_e32 v16, 1.0, v16
	v_mul_f32_e32 v17, v23, v44
	v_mul_f32_e32 v21, v21, v44
	v_lshrrev_b32_e32 v24, 16, v25
	v_cvt_pk_bf16_f32 v17, v17, v21
	v_mul_f32_e32 v21, v67, v22
	v_mul_f32_e32 v16, v67, v16
	v_cvt_pk_bf16_f32 v16, v21, v16
	v_perm_b32 v63, v63, v62, s7
	v_and_or_b32 v21, v16, s13, v24
	v_perm_b32 v62, v61, v60, s7
	v_perm_b32 v61, v59, v58, s7
	v_perm_b32 v60, v57, v55, s7
	v_perm_b32 v49, v52, v50, s7
	v_perm_b32 v48, v47, v45, s7
	v_perm_b32 v47, v43, v41, s7
	v_perm_b32 v46, v37, v35, s7
	ds_write_b16 v182, v17 offset:1008
	ds_write_b16_d16_hi v182, v17 offset:10224
	ds_write_b16 v182, v16 offset:19440
	ds_write_b128 v154, v[18:21] offset:27648
	ds_write_b128 v155, v[46:49] offset:36864
	ds_write_b128 v183, v[60:63] offset:36880
	s_waitcnt lgkmcnt(0)
	s_barrier
	v_add_u32_e32 v16, v127, v101
	v_add_u32_e32 v17, v127, v119
	ds_read_b128 v[56:59], v16
	ds_read_b128 v[60:63], v17
	v_add_u32_e32 v16, v127, v120
	v_add_u32_e32 v17, v127, v121
	ds_read_b128 v[64:67], v16
	ds_read_b128 v[68:71], v17
	ds_read_b128 v[72:75], v156 offset:18432
	ds_read_b128 v[44:47], v156 offset:18496
	ds_read_b128 v[24:27], v173 offset:9216
	ds_read_b128 v[52:55], v173 offset:9280
	ds_read_b128 v[80:83], v173 offset:11520
	ds_read_b128 v[48:51], v173 offset:11584
	ds_read_b128 v[76:79], v156
	ds_read_b128 v[16:19], v156 offset:64
	ds_read_b128 v[40:43], v139
	ds_read_b128 v[36:39], v140
	ds_read_b128 v[32:35], v141
	ds_read_b128 v[20:23], v142
	s_waitcnt lgkmcnt(0)
	v_mov_b32_e32 v145, v144
	v_mov_b32_e32 v146, v144
	v_mov_b32_e32 v147, v144
	v_mov_b64_e32 v[28:29], v[144:145]
	v_mov_b64_e32 v[30:31], v[146:147]
	s_and_saveexec_b64 s[26:27], s[44:45]
	s_cbranch_execz .LBB0_236
	s_waitcnt lgkmcnt(9)
	v_mfma_f32_16x16x32_bf16 v[28:31], v[72:75], v[24:27], 0
